# residual (EpiRes MODE0) epilogues rewritten by hand as two passes: statistics pass with permlane16/32 reduce-scatter and one 64-lane u64 atomic per 4 rows (2 instead of 8 atomics per tile, no LDS shuf
# baseline (speedup 1.0000x reference)
; __device__ __forceinline__ float ss_scale(const u64* ss, int row) { return __builtin_amdgcn_rsqf((float)ss[row] * (1.f / 4294967296.f / 1024.f) + EPS); }
; __device__ __forceinline__ unsigned pkbf(float lo, float hi) { typedef __bf16 bf2_t __attribute__((ext_vector_type(2))); f32x2 v = {lo, hi}; bf2_t b = __builtin_convertvector(v, bf2_t); return __builtin_bit_cast(unsigned, b); }
;     __device__ __forceinline__ void operator()(const f32x4 (&acc)[2][2][4][2], const pg8::Unit& u, int wr, int wc, int fr, int fq) const {
;     ...
;         for (int ai = 0; ai < 2; ++ai)
; #pragma unroll
;             for (int m = 0; m < 4; ++m) {
;                 const int row = row0 + ai * 128 + m * 16;
;                 float q = 0.f, qw = 0.f, sh = 1.f;
;                 if constexpr (MODE == 2) sh = ss_scale(rss, row);
; #pragma unroll
;                 for (int bj = 0; bj < 2; ++bj) {
;                     const int c = col0 + bj * 128;
;                     const u32x4 rb = *(const u32x4*)(hb + (size_t)row * DM + c);
;                     f32x4 r0 = {bflo(rb.x), bfhi(rb.x), bflo(rb.y), bfhi(rb.y)}, r1 = {bflo(rb.z), bfhi(rb.z), bflo(rb.w), bfhi(rb.w)};
;                     if constexpr (MODE == 2) { r0 = r0 * sh * g0[bj]; r1 = r1 * sh * g1[bj]; }
;                     const f32x4 v0 = r0 + acc[ai][bj][m][0], v1 = r1 + acc[ai][bj][m][1];
;                     if constexpr (WF32) { *(f32x4*)(out + (size_t)row * DM + c) = v0; *(f32x4*)(out + (size_t)row * DM + c + 4) = v1; }
;                     u32x4 w; w.x = pkbf(v0[0], v0[1]); w.y = pkbf(v0[2], v0[3]); w.z = pkbf(v1[0], v1[1]); w.w = pkbf(v1[2], v1[3]);
;                     *(u32x4*)(hb + (size_t)row * DM + c) = w;
;                     const f32x4 s0 = v0 * v0, s1 = v1 * v1;
;                     q += (s0[0] + s0[1]) + (s0[2] + s0[3]) + (s1[0] + s1[1]) + (s1[2] + s1[3]);
;                     if constexpr (MODE == 1) { const f32x4 t0 = s0 * g0[bj], t1 = s1 * g1[bj]; qw += (t0[0] + t0[1]) + (t0[2] + t0[3]) + (t1[0] + t1[1]) + (t1[2] + t1[3]); }
;                 }
;                 q += __shfl_xor(q, 16); q += __shfl_xor(q, 32);
.LBB0_358:
	v_lshl_add_u32 v146, s56, 8, v148
	v_ashrrev_i32_e32 v147, 31, v146
	v_lshl_or_b32 v144, s55, 8, v149
	v_lshlrev_b64 v[156:157], 11, v[146:147]
	v_lshl_add_u64 v[156:157], s[10:11], 0, v[156:157]
	v_ashrrev_i32_e32 v145, 31, v144
	v_lshl_add_u64 v[166:167], v[144:145], 1, v[156:157]
	v_mbcnt_lo_u32_b32 v222, -1, 0
	v_mbcnt_hi_u32_b32 v222, -1, v222
	v_and_b32_e32 v222, 48, v222
	v_add_u32_e32 v222, v222, v146
	v_mov_b32_e32 v223, 0
	s_mov_b32 s101, 0
	global_load_dwordx4 v[168:171], v[166:167], off
	global_load_dwordx4 v[172:175], v[166:167], off offset:256
	s_mov_b32 s100, 0x8000
	v_lshl_add_u64 v[158:159], v[166:167], 0, s[100:101]
	global_load_dwordx4 v[176:179], v[158:159], off
	global_load_dwordx4 v[180:183], v[158:159], off offset:256
	s_mov_b32 s100, 0x10000
	v_lshl_add_u64 v[158:159], v[166:167], 0, s[100:101]
	global_load_dwordx4 v[184:187], v[158:159], off
	global_load_dwordx4 v[188:191], v[158:159], off offset:256
	s_mov_b32 s100, 0x18000
	v_lshl_add_u64 v[158:159], v[166:167], 0, s[100:101]
	global_load_dwordx4 v[192:195], v[158:159], off
	global_load_dwordx4 v[200:203], v[158:159], off offset:256
	s_mov_b32 s100, 0x40000
	v_lshl_add_u64 v[158:159], v[166:167], 0, s[100:101]
	global_load_dwordx4 v[204:207], v[158:159], off
	global_load_dwordx4 v[208:211], v[158:159], off offset:256
	s_waitcnt vmcnt(8)
	v_lshlrev_b32_e32 v212, 16, v168
	v_and_b32_e32 v213, 0xffff0000, v168
	v_lshlrev_b32_e32 v214, 16, v169
	v_and_b32_e32 v215, 0xffff0000, v169
	v_lshlrev_b32_e32 v216, 16, v170
	v_and_b32_e32 v217, 0xffff0000, v170
	v_lshlrev_b32_e32 v218, 16, v171
	v_and_b32_e32 v219, 0xffff0000, v171
	v_pk_add_f32 v[124:125], v[124:125], v[212:213]
	v_pk_add_f32 v[126:127], v[126:127], v[214:215]
	v_pk_add_f32 v[120:121], v[120:121], v[216:217]
	v_pk_add_f32 v[122:123], v[122:123], v[218:219]
	v_lshlrev_b32_e32 v212, 16, v172
	v_and_b32_e32 v213, 0xffff0000, v172
	v_lshlrev_b32_e32 v214, 16, v173
	v_and_b32_e32 v215, 0xffff0000, v173
	v_lshlrev_b32_e32 v216, 16, v174
	v_and_b32_e32 v217, 0xffff0000, v174
	v_lshlrev_b32_e32 v218, 16, v175
	v_and_b32_e32 v219, 0xffff0000, v175
	v_pk_add_f32 v[116:117], v[116:117], v[212:213]
	v_pk_add_f32 v[118:119], v[118:119], v[214:215]
	v_pk_add_f32 v[112:113], v[112:113], v[216:217]
	v_pk_add_f32 v[114:115], v[114:115], v[218:219]
	s_mov_b32 s100, 0x48000
	v_lshl_add_u64 v[158:159], v[166:167], 0, s[100:101]
	global_load_dwordx4 v[168:171], v[158:159], off
	global_load_dwordx4 v[172:175], v[158:159], off offset:256
	v_pk_mul_f32 v[220:221], v[124:125], v[124:125]
	v_pk_fma_f32 v[220:221], v[126:127], v[126:127], v[220:221]
	v_pk_fma_f32 v[220:221], v[120:121], v[120:121], v[220:221]
	v_pk_fma_f32 v[220:221], v[122:123], v[122:123], v[220:221]
	v_pk_fma_f32 v[220:221], v[116:117], v[116:117], v[220:221]
	v_pk_fma_f32 v[220:221], v[118:119], v[118:119], v[220:221]
	v_pk_fma_f32 v[220:221], v[112:113], v[112:113], v[220:221]
	v_pk_fma_f32 v[220:221], v[114:115], v[114:115], v[220:221]
	v_add_f32_e32 v160, v220, v221
	s_waitcnt vmcnt(8)
	v_lshlrev_b32_e32 v212, 16, v176
	v_and_b32_e32 v213, 0xffff0000, v176
	v_lshlrev_b32_e32 v214, 16, v177
	v_and_b32_e32 v215, 0xffff0000, v177
	v_lshlrev_b32_e32 v216, 16, v178
	v_and_b32_e32 v217, 0xffff0000, v178
	v_lshlrev_b32_e32 v218, 16, v179
	v_and_b32_e32 v219, 0xffff0000, v179
	v_pk_add_f32 v[108:109], v[108:109], v[212:213]
	v_pk_add_f32 v[110:111], v[110:111], v[214:215]
	v_pk_add_f32 v[104:105], v[104:105], v[216:217]
	v_pk_add_f32 v[106:107], v[106:107], v[218:219]
	v_lshlrev_b32_e32 v212, 16, v180
	v_and_b32_e32 v213, 0xffff0000, v180
	v_lshlrev_b32_e32 v214, 16, v181
	v_and_b32_e32 v215, 0xffff0000, v181
	v_lshlrev_b32_e32 v216, 16, v182
	v_and_b32_e32 v217, 0xffff0000, v182
	v_lshlrev_b32_e32 v218, 16, v183
	v_and_b32_e32 v219, 0xffff0000, v183
	v_pk_add_f32 v[100:101], v[100:101], v[212:213]
	v_pk_add_f32 v[102:103], v[102:103], v[214:215]
	v_pk_add_f32 v[96:97], v[96:97], v[216:217]
	v_pk_add_f32 v[98:99], v[98:99], v[218:219]
	s_mov_b32 s100, 0x50000
	v_lshl_add_u64 v[158:159], v[166:167], 0, s[100:101]
	global_load_dwordx4 v[176:179], v[158:159], off
	global_load_dwordx4 v[180:183], v[158:159], off offset:256
	v_pk_mul_f32 v[220:221], v[108:109], v[108:109]
	v_pk_fma_f32 v[220:221], v[110:111], v[110:111], v[220:221]
	v_pk_fma_f32 v[220:221], v[104:105], v[104:105], v[220:221]
	v_pk_fma_f32 v[220:221], v[106:107], v[106:107], v[220:221]
	v_pk_fma_f32 v[220:221], v[100:101], v[100:101], v[220:221]
	v_pk_fma_f32 v[220:221], v[102:103], v[102:103], v[220:221]
	v_pk_fma_f32 v[220:221], v[96:97], v[96:97], v[220:221]
	v_pk_fma_f32 v[220:221], v[98:99], v[98:99], v[220:221]
	v_add_f32_e32 v161, v220, v221
	s_waitcnt vmcnt(8)
	v_lshlrev_b32_e32 v212, 16, v184
	v_and_b32_e32 v213, 0xffff0000, v184
	v_lshlrev_b32_e32 v214, 16, v185
	v_and_b32_e32 v215, 0xffff0000, v185
	v_lshlrev_b32_e32 v216, 16, v186
	v_and_b32_e32 v217, 0xffff0000, v186
	v_lshlrev_b32_e32 v218, 16, v187
	v_and_b32_e32 v219, 0xffff0000, v187
	v_pk_add_f32 v[92:93], v[92:93], v[212:213]
	v_pk_add_f32 v[94:95], v[94:95], v[214:215]
	v_pk_add_f32 v[88:89], v[88:89], v[216:217]
	v_pk_add_f32 v[90:91], v[90:91], v[218:219]
	v_lshlrev_b32_e32 v212, 16, v188
	v_and_b32_e32 v213, 0xffff0000, v188
	v_lshlrev_b32_e32 v214, 16, v189
	v_and_b32_e32 v215, 0xffff0000, v189
	v_lshlrev_b32_e32 v216, 16, v190
	v_and_b32_e32 v217, 0xffff0000, v190
	v_lshlrev_b32_e32 v218, 16, v191
	v_and_b32_e32 v219, 0xffff0000, v191
	v_pk_add_f32 v[84:85], v[84:85], v[212:213]
	v_pk_add_f32 v[86:87], v[86:87], v[214:215]
	v_pk_add_f32 v[80:81], v[80:81], v[216:217]
	v_pk_add_f32 v[82:83], v[82:83], v[218:219]
	s_mov_b32 s100, 0x58000
	v_lshl_add_u64 v[158:159], v[166:167], 0, s[100:101]
	global_load_dwordx4 v[184:187], v[158:159], off
	global_load_dwordx4 v[188:191], v[158:159], off offset:256
	v_pk_mul_f32 v[220:221], v[92:93], v[92:93]
	v_pk_fma_f32 v[220:221], v[94:95], v[94:95], v[220:221]
	v_pk_fma_f32 v[220:221], v[88:89], v[88:89], v[220:221]
	v_pk_fma_f32 v[220:221], v[90:91], v[90:91], v[220:221]
	v_pk_fma_f32 v[220:221], v[84:85], v[84:85], v[220:221]
	v_pk_fma_f32 v[220:221], v[86:87], v[86:87], v[220:221]
	v_pk_fma_f32 v[220:221], v[80:81], v[80:81], v[220:221]
	v_pk_fma_f32 v[220:221], v[82:83], v[82:83], v[220:221]
	v_add_f32_e32 v162, v220, v221
	s_waitcnt vmcnt(8)
; __device__ __forceinline__ float ss_scale(const u64* ss, int row) { return __builtin_amdgcn_rsqf((float)ss[row] * (1.f / 4294967296.f / 1024.f) + EPS); }
; __device__ __forceinline__ u64 ss_fix(float q) { return (u64)(q * 4294967296.f); }
;     __device__ __forceinline__ void operator()(const f32x4 (&acc)[2][2][4][2], const pg8::Unit& u, int wr, int wc, int fr, int fq) const {
;     ...
;         for (int ai = 0; ai < 2; ++ai)
; #pragma unroll
;             for (int m = 0; m < 4; ++m) {
;                 const int row = row0 + ai * 128 + m * 16;
;                 float q = 0.f, qw = 0.f, sh = 1.f;
;                 if constexpr (MODE == 2) sh = ss_scale(rss, row);
; #pragma unroll
;                 for (int bj = 0; bj < 2; ++bj) {
;                     const int c = col0 + bj * 128;
;                     const u32x4 rb = *(const u32x4*)(hb + (size_t)row * DM + c);
;                     f32x4 r0 = {bflo(rb.x), bfhi(rb.x), bflo(rb.y), bfhi(rb.y)}, r1 = {bflo(rb.z), bfhi(rb.z), bflo(rb.w), bfhi(rb.w)};
;                     if constexpr (MODE == 2) { r0 = r0 * sh * g0[bj]; r1 = r1 * sh * g1[bj]; }
;                     const f32x4 v0 = r0 + acc[ai][bj][m][0], v1 = r1 + acc[ai][bj][m][1];
;                     if constexpr (WF32) { *(f32x4*)(out + (size_t)row * DM + c) = v0; *(f32x4*)(out + (size_t)row * DM + c + 4) = v1; }
;                     u32x4 w; w.x = pkbf(v0[0], v0[1]); w.y = pkbf(v0[2], v0[3]); w.z = pkbf(v1[0], v1[1]); w.w = pkbf(v1[2], v1[3]);
;                     *(u32x4*)(hb + (size_t)row * DM + c) = w;
;                     const f32x4 s0 = v0 * v0, s1 = v1 * v1;
;                     q += (s0[0] + s0[1]) + (s0[2] + s0[3]) + (s1[0] + s1[1]) + (s1[2] + s1[3]);
;                     if constexpr (MODE == 1) { const f32x4 t0 = s0 * g0[bj], t1 = s1 * g1[bj]; qw += (t0[0] + t0[1]) + (t0[2] + t0[3]) + (t1[0] + t1[1]) + (t1[2] + t1[3]); }
;                 }
;                 q += __shfl_xor(q, 16); q += __shfl_xor(q, 32);
;                 if constexpr (MODE == 1) { qw += __shfl_xor(qw, 16); qw += __shfl_xor(qw, 32); }
;                 if (fq == 0) {
;                     __hip_atomic_fetch_add(ssn + row, ss_fix(q), __ATOMIC_RELAXED, __HIP_MEMORY_SCOPE_AGENT);
;                     if constexpr (MODE == 1) __hip_atomic_fetch_add(ssw + row, ss_fix(qw), __ATOMIC_RELAXED, __HIP_MEMORY_SCOPE_AGENT);
	v_lshlrev_b32_e32 v212, 16, v192
	v_and_b32_e32 v213, 0xffff0000, v192
	v_lshlrev_b32_e32 v214, 16, v193
	v_and_b32_e32 v215, 0xffff0000, v193
	v_lshlrev_b32_e32 v216, 16, v194
	v_and_b32_e32 v217, 0xffff0000, v194
	v_lshlrev_b32_e32 v218, 16, v195
	v_and_b32_e32 v219, 0xffff0000, v195
	v_pk_add_f32 v[76:77], v[76:77], v[212:213]
	v_pk_add_f32 v[78:79], v[78:79], v[214:215]
	v_pk_add_f32 v[72:73], v[72:73], v[216:217]
	v_pk_add_f32 v[74:75], v[74:75], v[218:219]
	v_lshlrev_b32_e32 v212, 16, v200
	v_and_b32_e32 v213, 0xffff0000, v200
	v_lshlrev_b32_e32 v214, 16, v201
	v_and_b32_e32 v215, 0xffff0000, v201
	v_lshlrev_b32_e32 v216, 16, v202
	v_and_b32_e32 v217, 0xffff0000, v202
	v_lshlrev_b32_e32 v218, 16, v203
	v_and_b32_e32 v219, 0xffff0000, v203
	v_pk_add_f32 v[68:69], v[68:69], v[212:213]
	v_pk_add_f32 v[70:71], v[70:71], v[214:215]
	v_pk_add_f32 v[64:65], v[64:65], v[216:217]
	v_pk_add_f32 v[66:67], v[66:67], v[218:219]
	v_pk_mul_f32 v[220:221], v[76:77], v[76:77]
	v_pk_fma_f32 v[220:221], v[78:79], v[78:79], v[220:221]
	v_pk_fma_f32 v[220:221], v[72:73], v[72:73], v[220:221]
	v_pk_fma_f32 v[220:221], v[74:75], v[74:75], v[220:221]
	v_pk_fma_f32 v[220:221], v[68:69], v[68:69], v[220:221]
	v_pk_fma_f32 v[220:221], v[70:71], v[70:71], v[220:221]
	v_pk_fma_f32 v[220:221], v[64:65], v[64:65], v[220:221]
	v_pk_fma_f32 v[220:221], v[66:67], v[66:67], v[220:221]
	v_add_f32_e32 v163, v220, v221
	s_nop 1
	v_permlane16_swap_b32_e32 v160, v161
	v_permlane16_swap_b32_e32 v162, v163
	v_add_f32_e32 v160, v160, v161
	v_add_f32_e32 v162, v162, v163
	s_nop 1
	v_permlane32_swap_b32_e32 v160, v162
	v_add_f32_e32 v160, v160, v162
	v_mul_f32_e32 v226, 0x4f800000, v160
	v_trunc_f32_e32 v226, v226
	v_mul_f32_e32 v227, 0x2f800000, v226
	v_floor_f32_e32 v227, v227
	v_fmac_f32_e32 v226, 0xcf800000, v227
	v_cvt_u32_f32_e32 v226, v226
	v_cvt_u32_f32_e32 v227, v227
	v_lshl_add_u64 v[224:225], v[222:223], 3, s[12:13]
	global_atomic_add_x2 v[224:225], v[226:227], off
	s_waitcnt vmcnt(7)
	v_lshlrev_b32_e32 v212, 16, v204
	v_and_b32_e32 v213, 0xffff0000, v204
	v_lshlrev_b32_e32 v214, 16, v205
	v_and_b32_e32 v215, 0xffff0000, v205
	v_lshlrev_b32_e32 v216, 16, v206
	v_and_b32_e32 v217, 0xffff0000, v206
	v_lshlrev_b32_e32 v218, 16, v207
	v_and_b32_e32 v219, 0xffff0000, v207
	v_pk_add_f32 v[60:61], v[60:61], v[212:213]
	v_pk_add_f32 v[62:63], v[62:63], v[214:215]
	v_pk_add_f32 v[56:57], v[56:57], v[216:217]
	v_pk_add_f32 v[58:59], v[58:59], v[218:219]
	v_lshlrev_b32_e32 v212, 16, v208
	v_and_b32_e32 v213, 0xffff0000, v208
	v_lshlrev_b32_e32 v214, 16, v209
	v_and_b32_e32 v215, 0xffff0000, v209
	v_lshlrev_b32_e32 v216, 16, v210
	v_and_b32_e32 v217, 0xffff0000, v210
	v_lshlrev_b32_e32 v218, 16, v211
	v_and_b32_e32 v219, 0xffff0000, v211
	v_pk_add_f32 v[52:53], v[52:53], v[212:213]
	v_pk_add_f32 v[54:55], v[54:55], v[214:215]
	v_pk_add_f32 v[48:49], v[48:49], v[216:217]
	v_pk_add_f32 v[50:51], v[50:51], v[218:219]
	v_pk_mul_f32 v[220:221], v[60:61], v[60:61]
	v_pk_fma_f32 v[220:221], v[62:63], v[62:63], v[220:221]
	v_pk_fma_f32 v[220:221], v[56:57], v[56:57], v[220:221]
	v_pk_fma_f32 v[220:221], v[58:59], v[58:59], v[220:221]
	v_pk_fma_f32 v[220:221], v[52:53], v[52:53], v[220:221]
	v_pk_fma_f32 v[220:221], v[54:55], v[54:55], v[220:221]
	v_pk_fma_f32 v[220:221], v[48:49], v[48:49], v[220:221]
	v_pk_fma_f32 v[220:221], v[50:51], v[50:51], v[220:221]
	v_add_f32_e32 v160, v220, v221
	s_waitcnt vmcnt(5)
	v_lshlrev_b32_e32 v212, 16, v168
	v_and_b32_e32 v213, 0xffff0000, v168
	v_lshlrev_b32_e32 v214, 16, v169
	v_and_b32_e32 v215, 0xffff0000, v169
	v_lshlrev_b32_e32 v216, 16, v170
	v_and_b32_e32 v217, 0xffff0000, v170
	v_lshlrev_b32_e32 v218, 16, v171
	v_and_b32_e32 v219, 0xffff0000, v171
	v_pk_add_f32 v[44:45], v[44:45], v[212:213]
	v_pk_add_f32 v[46:47], v[46:47], v[214:215]
	v_pk_add_f32 v[40:41], v[40:41], v[216:217]
	v_pk_add_f32 v[42:43], v[42:43], v[218:219]
	v_lshlrev_b32_e32 v212, 16, v172
	v_and_b32_e32 v213, 0xffff0000, v172
	v_lshlrev_b32_e32 v214, 16, v173
	v_and_b32_e32 v215, 0xffff0000, v173
	v_lshlrev_b32_e32 v216, 16, v174
	v_and_b32_e32 v217, 0xffff0000, v174
	v_lshlrev_b32_e32 v218, 16, v175
	v_and_b32_e32 v219, 0xffff0000, v175
	v_pk_add_f32 v[36:37], v[36:37], v[212:213]
	v_pk_add_f32 v[38:39], v[38:39], v[214:215]
	v_pk_add_f32 v[32:33], v[32:33], v[216:217]
	v_pk_add_f32 v[34:35], v[34:35], v[218:219]
	v_pk_mul_f32 v[220:221], v[44:45], v[44:45]
	v_pk_fma_f32 v[220:221], v[46:47], v[46:47], v[220:221]
	v_pk_fma_f32 v[220:221], v[40:41], v[40:41], v[220:221]
	v_pk_fma_f32 v[220:221], v[42:43], v[42:43], v[220:221]
	v_pk_fma_f32 v[220:221], v[36:37], v[36:37], v[220:221]
	v_pk_fma_f32 v[220:221], v[38:39], v[38:39], v[220:221]
	v_pk_fma_f32 v[220:221], v[32:33], v[32:33], v[220:221]
	v_pk_fma_f32 v[220:221], v[34:35], v[34:35], v[220:221]
	v_add_f32_e32 v161, v220, v221
	s_waitcnt vmcnt(3)
	v_lshlrev_b32_e32 v212, 16, v176
	v_and_b32_e32 v213, 0xffff0000, v176
	v_lshlrev_b32_e32 v214, 16, v177
	v_and_b32_e32 v215, 0xffff0000, v177
	v_lshlrev_b32_e32 v216, 16, v178
	v_and_b32_e32 v217, 0xffff0000, v178
	v_lshlrev_b32_e32 v218, 16, v179
	v_and_b32_e32 v219, 0xffff0000, v179
	v_pk_add_f32 v[28:29], v[28:29], v[212:213]
	v_pk_add_f32 v[30:31], v[30:31], v[214:215]
	v_pk_add_f32 v[24:25], v[24:25], v[216:217]
	v_pk_add_f32 v[26:27], v[26:27], v[218:219]
	v_lshlrev_b32_e32 v212, 16, v180
	v_and_b32_e32 v213, 0xffff0000, v180
	v_lshlrev_b32_e32 v214, 16, v181
	v_and_b32_e32 v215, 0xffff0000, v181
	v_lshlrev_b32_e32 v216, 16, v182
	v_and_b32_e32 v217, 0xffff0000, v182
	v_lshlrev_b32_e32 v218, 16, v183
	v_and_b32_e32 v219, 0xffff0000, v183
	v_pk_add_f32 v[20:21], v[20:21], v[212:213]
	v_pk_add_f32 v[22:23], v[22:23], v[214:215]
	v_pk_add_f32 v[16:17], v[16:17], v[216:217]
	v_pk_add_f32 v[18:19], v[18:19], v[218:219]
	v_pk_mul_f32 v[220:221], v[28:29], v[28:29]
	v_pk_fma_f32 v[220:221], v[30:31], v[30:31], v[220:221]
	v_pk_fma_f32 v[220:221], v[24:25], v[24:25], v[220:221]
	v_pk_fma_f32 v[220:221], v[26:27], v[26:27], v[220:221]
	v_pk_fma_f32 v[220:221], v[20:21], v[20:21], v[220:221]
	v_pk_fma_f32 v[220:221], v[22:23], v[22:23], v[220:221]
	v_pk_fma_f32 v[220:221], v[16:17], v[16:17], v[220:221]
	v_pk_fma_f32 v[220:221], v[18:19], v[18:19], v[220:221]
	v_add_f32_e32 v162, v220, v221
	s_waitcnt vmcnt(1)
; __device__ __forceinline__ u64 ss_fix(float q) { return (u64)(q * 4294967296.f); }
; __device__ __forceinline__ unsigned pkbf(float lo, float hi) { typedef __bf16 bf2_t __attribute__((ext_vector_type(2))); f32x2 v = {lo, hi}; bf2_t b = __builtin_convertvector(v, bf2_t); return __builtin_bit_cast(unsigned, b); }
;     __device__ __forceinline__ void operator()(const f32x4 (&acc)[2][2][4][2], const pg8::Unit& u, int wr, int wc, int fr, int fq) const {
;     ...
;                 for (int bj = 0; bj < 2; ++bj) {
;                     const int c = col0 + bj * 128;
;                     const u32x4 rb = *(const u32x4*)(hb + (size_t)row * DM + c);
;                     f32x4 r0 = {bflo(rb.x), bfhi(rb.x), bflo(rb.y), bfhi(rb.y)}, r1 = {bflo(rb.z), bfhi(rb.z), bflo(rb.w), bfhi(rb.w)};
;                     if constexpr (MODE == 2) { r0 = r0 * sh * g0[bj]; r1 = r1 * sh * g1[bj]; }
;                     const f32x4 v0 = r0 + acc[ai][bj][m][0], v1 = r1 + acc[ai][bj][m][1];
;                     if constexpr (WF32) { *(f32x4*)(out + (size_t)row * DM + c) = v0; *(f32x4*)(out + (size_t)row * DM + c + 4) = v1; }
;                     u32x4 w; w.x = pkbf(v0[0], v0[1]); w.y = pkbf(v0[2], v0[3]); w.z = pkbf(v1[0], v1[1]); w.w = pkbf(v1[2], v1[3]);
;                     *(u32x4*)(hb + (size_t)row * DM + c) = w;
;                     const f32x4 s0 = v0 * v0, s1 = v1 * v1;
;                     q += (s0[0] + s0[1]) + (s0[2] + s0[3]) + (s1[0] + s1[1]) + (s1[2] + s1[3]);
;                     if constexpr (MODE == 1) { const f32x4 t0 = s0 * g0[bj], t1 = s1 * g1[bj]; qw += (t0[0] + t0[1]) + (t0[2] + t0[3]) + (t1[0] + t1[1]) + (t1[2] + t1[3]); }
;                 }
;                 q += __shfl_xor(q, 16); q += __shfl_xor(q, 32);
;                 if constexpr (MODE == 1) { qw += __shfl_xor(qw, 16); qw += __shfl_xor(qw, 32); }
;                 if (fq == 0) {
;                     __hip_atomic_fetch_add(ssn + row, ss_fix(q), __ATOMIC_RELAXED, __HIP_MEMORY_SCOPE_AGENT);
;                     if constexpr (MODE == 1) __hip_atomic_fetch_add(ssw + row, ss_fix(qw), __ATOMIC_RELAXED, __HIP_MEMORY_SCOPE_AGENT);
	v_lshlrev_b32_e32 v212, 16, v184
	v_and_b32_e32 v213, 0xffff0000, v184
	v_lshlrev_b32_e32 v214, 16, v185
	v_and_b32_e32 v215, 0xffff0000, v185
	v_lshlrev_b32_e32 v216, 16, v186
	v_and_b32_e32 v217, 0xffff0000, v186
	v_lshlrev_b32_e32 v218, 16, v187
	v_and_b32_e32 v219, 0xffff0000, v187
	v_pk_add_f32 v[12:13], v[12:13], v[212:213]
	v_pk_add_f32 v[14:15], v[14:15], v[214:215]
	v_pk_add_f32 v[8:9], v[8:9], v[216:217]
	v_pk_add_f32 v[10:11], v[10:11], v[218:219]
	v_lshlrev_b32_e32 v212, 16, v188
	v_and_b32_e32 v213, 0xffff0000, v188
	v_lshlrev_b32_e32 v214, 16, v189
	v_and_b32_e32 v215, 0xffff0000, v189
	v_lshlrev_b32_e32 v216, 16, v190
	v_and_b32_e32 v217, 0xffff0000, v190
	v_lshlrev_b32_e32 v218, 16, v191
	v_and_b32_e32 v219, 0xffff0000, v191
	v_pk_add_f32 v[4:5], v[4:5], v[212:213]
	v_pk_add_f32 v[6:7], v[6:7], v[214:215]
	v_pk_add_f32 v[0:1], v[0:1], v[216:217]
	v_pk_add_f32 v[2:3], v[2:3], v[218:219]
	v_pk_mul_f32 v[220:221], v[12:13], v[12:13]
	v_pk_fma_f32 v[220:221], v[14:15], v[14:15], v[220:221]
	v_pk_fma_f32 v[220:221], v[8:9], v[8:9], v[220:221]
	v_pk_fma_f32 v[220:221], v[10:11], v[10:11], v[220:221]
	v_pk_fma_f32 v[220:221], v[4:5], v[4:5], v[220:221]
	v_pk_fma_f32 v[220:221], v[6:7], v[6:7], v[220:221]
	v_pk_fma_f32 v[220:221], v[0:1], v[0:1], v[220:221]
	v_pk_fma_f32 v[220:221], v[2:3], v[2:3], v[220:221]
	v_add_f32_e32 v163, v220, v221
	s_nop 1
	v_permlane16_swap_b32_e32 v160, v161
	v_permlane16_swap_b32_e32 v162, v163
	v_add_f32_e32 v160, v160, v161
	v_add_f32_e32 v162, v162, v163
	s_nop 1
	v_permlane32_swap_b32_e32 v160, v162
	v_add_f32_e32 v160, v160, v162
	v_mul_f32_e32 v226, 0x4f800000, v160
	v_trunc_f32_e32 v226, v226
	v_mul_f32_e32 v227, 0x2f800000, v226
	v_floor_f32_e32 v227, v227
	v_fmac_f32_e32 v226, 0xcf800000, v227
	v_cvt_u32_f32_e32 v226, v226
	v_cvt_u32_f32_e32 v227, v227
	v_add_u32_e32 v222, 0x80, v222
	v_lshl_add_u64 v[224:225], v[222:223], 3, s[12:13]
	global_atomic_add_x2 v[224:225], v[226:227], off
	v_cvt_pk_bf16_f32 v124, v124, v125
	v_cvt_pk_bf16_f32 v125, v126, v127
	v_cvt_pk_bf16_f32 v126, v120, v121
	v_cvt_pk_bf16_f32 v127, v122, v123
	v_cvt_pk_bf16_f32 v116, v116, v117
	v_cvt_pk_bf16_f32 v117, v118, v119
	v_cvt_pk_bf16_f32 v118, v112, v113
	v_cvt_pk_bf16_f32 v119, v114, v115
	global_store_dwordx4 v[166:167], v[124:127], off
	global_store_dwordx4 v[166:167], v[116:119], off offset:256
	v_cvt_pk_bf16_f32 v108, v108, v109
	v_cvt_pk_bf16_f32 v109, v110, v111
	v_cvt_pk_bf16_f32 v110, v104, v105
	v_cvt_pk_bf16_f32 v111, v106, v107
	v_cvt_pk_bf16_f32 v100, v100, v101
	v_cvt_pk_bf16_f32 v101, v102, v103
	v_cvt_pk_bf16_f32 v102, v96, v97
	v_cvt_pk_bf16_f32 v103, v98, v99
	s_mov_b32 s100, 0x8000
	v_lshl_add_u64 v[158:159], v[166:167], 0, s[100:101]
	global_store_dwordx4 v[158:159], v[108:111], off
	global_store_dwordx4 v[158:159], v[100:103], off offset:256
	v_cvt_pk_bf16_f32 v92, v92, v93
	v_cvt_pk_bf16_f32 v93, v94, v95
	v_cvt_pk_bf16_f32 v94, v88, v89
	v_cvt_pk_bf16_f32 v95, v90, v91
	v_cvt_pk_bf16_f32 v84, v84, v85
	v_cvt_pk_bf16_f32 v85, v86, v87
	v_cvt_pk_bf16_f32 v86, v80, v81
	v_cvt_pk_bf16_f32 v87, v82, v83
	s_mov_b32 s100, 0x10000
	v_lshl_add_u64 v[158:159], v[166:167], 0, s[100:101]
	global_store_dwordx4 v[158:159], v[92:95], off
	global_store_dwordx4 v[158:159], v[84:87], off offset:256
	v_cvt_pk_bf16_f32 v76, v76, v77
	v_cvt_pk_bf16_f32 v77, v78, v79
	v_cvt_pk_bf16_f32 v78, v72, v73
	v_cvt_pk_bf16_f32 v79, v74, v75
	v_cvt_pk_bf16_f32 v68, v68, v69
	v_cvt_pk_bf16_f32 v69, v70, v71
	v_cvt_pk_bf16_f32 v70, v64, v65
	v_cvt_pk_bf16_f32 v71, v66, v67
	s_mov_b32 s100, 0x18000
	v_lshl_add_u64 v[158:159], v[166:167], 0, s[100:101]
	global_store_dwordx4 v[158:159], v[76:79], off
	global_store_dwordx4 v[158:159], v[68:71], off offset:256
	v_cvt_pk_bf16_f32 v60, v60, v61
	v_cvt_pk_bf16_f32 v61, v62, v63
	v_cvt_pk_bf16_f32 v62, v56, v57
	v_cvt_pk_bf16_f32 v63, v58, v59
	v_cvt_pk_bf16_f32 v52, v52, v53
	v_cvt_pk_bf16_f32 v53, v54, v55
	v_cvt_pk_bf16_f32 v54, v48, v49
	v_cvt_pk_bf16_f32 v55, v50, v51
	s_mov_b32 s100, 0x40000
	v_lshl_add_u64 v[158:159], v[166:167], 0, s[100:101]
	global_store_dwordx4 v[158:159], v[60:63], off
	global_store_dwordx4 v[158:159], v[52:55], off offset:256
	v_cvt_pk_bf16_f32 v44, v44, v45
	v_cvt_pk_bf16_f32 v45, v46, v47
	v_cvt_pk_bf16_f32 v46, v40, v41
	v_cvt_pk_bf16_f32 v47, v42, v43
	v_cvt_pk_bf16_f32 v36, v36, v37
	v_cvt_pk_bf16_f32 v37, v38, v39
	v_cvt_pk_bf16_f32 v38, v32, v33
	v_cvt_pk_bf16_f32 v39, v34, v35
	s_mov_b32 s100, 0x48000
	v_lshl_add_u64 v[158:159], v[166:167], 0, s[100:101]
	global_store_dwordx4 v[158:159], v[44:47], off
	global_store_dwordx4 v[158:159], v[36:39], off offset:256
	v_cvt_pk_bf16_f32 v28, v28, v29
	v_cvt_pk_bf16_f32 v29, v30, v31
	v_cvt_pk_bf16_f32 v30, v24, v25
	v_cvt_pk_bf16_f32 v31, v26, v27
	v_cvt_pk_bf16_f32 v20, v20, v21
	v_cvt_pk_bf16_f32 v21, v22, v23
	v_cvt_pk_bf16_f32 v22, v16, v17
	v_cvt_pk_bf16_f32 v23, v18, v19
	s_mov_b32 s100, 0x50000
	v_lshl_add_u64 v[158:159], v[166:167], 0, s[100:101]
	global_store_dwordx4 v[158:159], v[28:31], off
	global_store_dwordx4 v[158:159], v[20:23], off offset:256
	v_cvt_pk_bf16_f32 v12, v12, v13
	v_cvt_pk_bf16_f32 v13, v14, v15
	v_cvt_pk_bf16_f32 v14, v8, v9
	v_cvt_pk_bf16_f32 v15, v10, v11
	v_cvt_pk_bf16_f32 v4, v4, v5
	v_cvt_pk_bf16_f32 v5, v6, v7
	v_cvt_pk_bf16_f32 v6, v0, v1
	v_cvt_pk_bf16_f32 v7, v2, v3
	s_mov_b32 s100, 0x58000
	v_lshl_add_u64 v[158:159], v[166:167], 0, s[100:101]
	global_store_dwordx4 v[158:159], v[12:15], off
	global_store_dwordx4 v[158:159], v[4:7], off offset:256
	s_mov_b64 s[22:23], exec

; __device__ __forceinline__ float ss_scale(const u64* ss, int row) { return __builtin_amdgcn_rsqf((float)ss[row] * (1.f / 4294967296.f / 1024.f) + EPS); }
; __device__ __forceinline__ unsigned pkbf(float lo, float hi) { typedef __bf16 bf2_t __attribute__((ext_vector_type(2))); f32x2 v = {lo, hi}; bf2_t b = __builtin_convertvector(v, bf2_t); return __builtin_bit_cast(unsigned, b); }
;     __device__ __forceinline__ void operator()(const f32x4 (&acc)[2][2][4][2], const pg8::Unit& u, int wr, int wc, int fr, int fq) const {
;     ...
;         for (int ai = 0; ai < 2; ++ai)
; #pragma unroll
;             for (int m = 0; m < 4; ++m) {
;                 const int row = row0 + ai * 128 + m * 16;
;                 float q = 0.f, qw = 0.f, sh = 1.f;
;                 if constexpr (MODE == 2) sh = ss_scale(rss, row);
; #pragma unroll
;                 for (int bj = 0; bj < 2; ++bj) {
;                     const int c = col0 + bj * 128;
;                     const u32x4 rb = *(const u32x4*)(hb + (size_t)row * DM + c);
;                     f32x4 r0 = {bflo(rb.x), bfhi(rb.x), bflo(rb.y), bfhi(rb.y)}, r1 = {bflo(rb.z), bfhi(rb.z), bflo(rb.w), bfhi(rb.w)};
;                     if constexpr (MODE == 2) { r0 = r0 * sh * g0[bj]; r1 = r1 * sh * g1[bj]; }
;                     const f32x4 v0 = r0 + acc[ai][bj][m][0], v1 = r1 + acc[ai][bj][m][1];
;                     if constexpr (WF32) { *(f32x4*)(out + (size_t)row * DM + c) = v0; *(f32x4*)(out + (size_t)row * DM + c + 4) = v1; }
;                     u32x4 w; w.x = pkbf(v0[0], v0[1]); w.y = pkbf(v0[2], v0[3]); w.z = pkbf(v1[0], v1[1]); w.w = pkbf(v1[2], v1[3]);
;                     *(u32x4*)(hb + (size_t)row * DM + c) = w;
;                     const f32x4 s0 = v0 * v0, s1 = v1 * v1;
;                     q += (s0[0] + s0[1]) + (s0[2] + s0[3]) + (s1[0] + s1[1]) + (s1[2] + s1[3]);
;                     if constexpr (MODE == 1) { const f32x4 t0 = s0 * g0[bj], t1 = s1 * g1[bj]; qw += (t0[0] + t0[1]) + (t0[2] + t0[3]) + (t1[0] + t1[1]) + (t1[2] + t1[3]); }
;                 }
;                 q += __shfl_xor(q, 16); q += __shfl_xor(q, 32);
.LBB0_770:
	v_lshl_add_u32 v146, s57, 8, v148
	v_ashrrev_i32_e32 v147, 31, v146
	v_lshl_or_b32 v144, s26, 8, v149
	v_lshlrev_b64 v[156:157], 11, v[146:147]
	v_lshl_add_u64 v[156:157], s[10:11], 0, v[156:157]
	v_ashrrev_i32_e32 v145, 31, v144
	v_lshl_add_u64 v[166:167], v[144:145], 1, v[156:157]
	v_mbcnt_lo_u32_b32 v222, -1, 0
	v_mbcnt_hi_u32_b32 v222, -1, v222
	v_and_b32_e32 v222, 48, v222
	v_add_u32_e32 v222, v222, v146
	v_mov_b32_e32 v223, 0
	s_mov_b32 s101, 0
	global_load_dwordx4 v[168:171], v[166:167], off
	global_load_dwordx4 v[172:175], v[166:167], off offset:256
	s_mov_b32 s100, 0x8000
	v_lshl_add_u64 v[158:159], v[166:167], 0, s[100:101]
	global_load_dwordx4 v[176:179], v[158:159], off
	global_load_dwordx4 v[180:183], v[158:159], off offset:256
	s_mov_b32 s100, 0x10000
	v_lshl_add_u64 v[158:159], v[166:167], 0, s[100:101]
	global_load_dwordx4 v[184:187], v[158:159], off
	global_load_dwordx4 v[188:191], v[158:159], off offset:256
	s_mov_b32 s100, 0x18000
	v_lshl_add_u64 v[158:159], v[166:167], 0, s[100:101]
	global_load_dwordx4 v[192:195], v[158:159], off
	global_load_dwordx4 v[200:203], v[158:159], off offset:256
	s_mov_b32 s100, 0x40000
	v_lshl_add_u64 v[158:159], v[166:167], 0, s[100:101]
	global_load_dwordx4 v[204:207], v[158:159], off
	global_load_dwordx4 v[208:211], v[158:159], off offset:256
	s_waitcnt vmcnt(8)
	v_lshlrev_b32_e32 v212, 16, v168
	v_and_b32_e32 v213, 0xffff0000, v168
	v_lshlrev_b32_e32 v214, 16, v169
	v_and_b32_e32 v215, 0xffff0000, v169
	v_lshlrev_b32_e32 v216, 16, v170
	v_and_b32_e32 v217, 0xffff0000, v170
	v_lshlrev_b32_e32 v218, 16, v171
	v_and_b32_e32 v219, 0xffff0000, v171
	v_pk_add_f32 v[124:125], v[124:125], v[212:213]
	v_pk_add_f32 v[126:127], v[126:127], v[214:215]
	v_pk_add_f32 v[120:121], v[120:121], v[216:217]
	v_pk_add_f32 v[122:123], v[122:123], v[218:219]
	v_lshlrev_b32_e32 v212, 16, v172
	v_and_b32_e32 v213, 0xffff0000, v172
	v_lshlrev_b32_e32 v214, 16, v173
	v_and_b32_e32 v215, 0xffff0000, v173
	v_lshlrev_b32_e32 v216, 16, v174
	v_and_b32_e32 v217, 0xffff0000, v174
	v_lshlrev_b32_e32 v218, 16, v175
	v_and_b32_e32 v219, 0xffff0000, v175
	v_pk_add_f32 v[116:117], v[116:117], v[212:213]
	v_pk_add_f32 v[118:119], v[118:119], v[214:215]
	v_pk_add_f32 v[112:113], v[112:113], v[216:217]
	v_pk_add_f32 v[114:115], v[114:115], v[218:219]
	s_mov_b32 s100, 0x48000
	v_lshl_add_u64 v[158:159], v[166:167], 0, s[100:101]
	global_load_dwordx4 v[168:171], v[158:159], off
	global_load_dwordx4 v[172:175], v[158:159], off offset:256
	v_pk_mul_f32 v[220:221], v[124:125], v[124:125]
	v_pk_fma_f32 v[220:221], v[126:127], v[126:127], v[220:221]
	v_pk_fma_f32 v[220:221], v[120:121], v[120:121], v[220:221]
	v_pk_fma_f32 v[220:221], v[122:123], v[122:123], v[220:221]
	v_pk_fma_f32 v[220:221], v[116:117], v[116:117], v[220:221]
	v_pk_fma_f32 v[220:221], v[118:119], v[118:119], v[220:221]
	v_pk_fma_f32 v[220:221], v[112:113], v[112:113], v[220:221]
	v_pk_fma_f32 v[220:221], v[114:115], v[114:115], v[220:221]
	v_add_f32_e32 v160, v220, v221
	s_waitcnt vmcnt(8)
	v_lshlrev_b32_e32 v212, 16, v176
	v_and_b32_e32 v213, 0xffff0000, v176
	v_lshlrev_b32_e32 v214, 16, v177
	v_and_b32_e32 v215, 0xffff0000, v177
	v_lshlrev_b32_e32 v216, 16, v178
	v_and_b32_e32 v217, 0xffff0000, v178
	v_lshlrev_b32_e32 v218, 16, v179
	v_and_b32_e32 v219, 0xffff0000, v179
	v_pk_add_f32 v[108:109], v[108:109], v[212:213]
	v_pk_add_f32 v[110:111], v[110:111], v[214:215]
	v_pk_add_f32 v[104:105], v[104:105], v[216:217]
	v_pk_add_f32 v[106:107], v[106:107], v[218:219]
	v_lshlrev_b32_e32 v212, 16, v180
	v_and_b32_e32 v213, 0xffff0000, v180
	v_lshlrev_b32_e32 v214, 16, v181
	v_and_b32_e32 v215, 0xffff0000, v181
	v_lshlrev_b32_e32 v216, 16, v182
	v_and_b32_e32 v217, 0xffff0000, v182
	v_lshlrev_b32_e32 v218, 16, v183
	v_and_b32_e32 v219, 0xffff0000, v183
	v_pk_add_f32 v[100:101], v[100:101], v[212:213]
	v_pk_add_f32 v[102:103], v[102:103], v[214:215]
	v_pk_add_f32 v[96:97], v[96:97], v[216:217]
	v_pk_add_f32 v[98:99], v[98:99], v[218:219]
	s_mov_b32 s100, 0x50000
	v_lshl_add_u64 v[158:159], v[166:167], 0, s[100:101]
	global_load_dwordx4 v[176:179], v[158:159], off
	global_load_dwordx4 v[180:183], v[158:159], off offset:256
	v_pk_mul_f32 v[220:221], v[108:109], v[108:109]
	v_pk_fma_f32 v[220:221], v[110:111], v[110:111], v[220:221]
	v_pk_fma_f32 v[220:221], v[104:105], v[104:105], v[220:221]
	v_pk_fma_f32 v[220:221], v[106:107], v[106:107], v[220:221]
	v_pk_fma_f32 v[220:221], v[100:101], v[100:101], v[220:221]
	v_pk_fma_f32 v[220:221], v[102:103], v[102:103], v[220:221]
	v_pk_fma_f32 v[220:221], v[96:97], v[96:97], v[220:221]
	v_pk_fma_f32 v[220:221], v[98:99], v[98:99], v[220:221]
	v_add_f32_e32 v161, v220, v221
	s_waitcnt vmcnt(8)
	v_lshlrev_b32_e32 v212, 16, v184
	v_and_b32_e32 v213, 0xffff0000, v184
	v_lshlrev_b32_e32 v214, 16, v185
	v_and_b32_e32 v215, 0xffff0000, v185
	v_lshlrev_b32_e32 v216, 16, v186
	v_and_b32_e32 v217, 0xffff0000, v186
	v_lshlrev_b32_e32 v218, 16, v187
	v_and_b32_e32 v219, 0xffff0000, v187
	v_pk_add_f32 v[92:93], v[92:93], v[212:213]
	v_pk_add_f32 v[94:95], v[94:95], v[214:215]
	v_pk_add_f32 v[88:89], v[88:89], v[216:217]
	v_pk_add_f32 v[90:91], v[90:91], v[218:219]
	v_lshlrev_b32_e32 v212, 16, v188
	v_and_b32_e32 v213, 0xffff0000, v188
	v_lshlrev_b32_e32 v214, 16, v189
	v_and_b32_e32 v215, 0xffff0000, v189
	v_lshlrev_b32_e32 v216, 16, v190
	v_and_b32_e32 v217, 0xffff0000, v190
	v_lshlrev_b32_e32 v218, 16, v191
	v_and_b32_e32 v219, 0xffff0000, v191
	v_pk_add_f32 v[84:85], v[84:85], v[212:213]
	v_pk_add_f32 v[86:87], v[86:87], v[214:215]
	v_pk_add_f32 v[80:81], v[80:81], v[216:217]
	v_pk_add_f32 v[82:83], v[82:83], v[218:219]
	s_mov_b32 s100, 0x58000
	v_lshl_add_u64 v[158:159], v[166:167], 0, s[100:101]
	global_load_dwordx4 v[184:187], v[158:159], off
	global_load_dwordx4 v[188:191], v[158:159], off offset:256
	v_pk_mul_f32 v[220:221], v[92:93], v[92:93]
	v_pk_fma_f32 v[220:221], v[94:95], v[94:95], v[220:221]
	v_pk_fma_f32 v[220:221], v[88:89], v[88:89], v[220:221]
	v_pk_fma_f32 v[220:221], v[90:91], v[90:91], v[220:221]
	v_pk_fma_f32 v[220:221], v[84:85], v[84:85], v[220:221]
	v_pk_fma_f32 v[220:221], v[86:87], v[86:87], v[220:221]
	v_pk_fma_f32 v[220:221], v[80:81], v[80:81], v[220:221]
	v_pk_fma_f32 v[220:221], v[82:83], v[82:83], v[220:221]
	v_add_f32_e32 v162, v220, v221
	s_waitcnt vmcnt(8)
; __device__ __forceinline__ float ss_scale(const u64* ss, int row) { return __builtin_amdgcn_rsqf((float)ss[row] * (1.f / 4294967296.f / 1024.f) + EPS); }
; __device__ __forceinline__ u64 ss_fix(float q) { return (u64)(q * 4294967296.f); }
;     __device__ __forceinline__ void operator()(const f32x4 (&acc)[2][2][4][2], const pg8::Unit& u, int wr, int wc, int fr, int fq) const {
;     ...
;                 const int row = row0 + ai * 128 + m * 16;
;                 float q = 0.f, qw = 0.f, sh = 1.f;
;                 if constexpr (MODE == 2) sh = ss_scale(rss, row);
; #pragma unroll
;                 for (int bj = 0; bj < 2; ++bj) {
;                     const int c = col0 + bj * 128;
;                     const u32x4 rb = *(const u32x4*)(hb + (size_t)row * DM + c);
;                     f32x4 r0 = {bflo(rb.x), bfhi(rb.x), bflo(rb.y), bfhi(rb.y)}, r1 = {bflo(rb.z), bfhi(rb.z), bflo(rb.w), bfhi(rb.w)};
;                     if constexpr (MODE == 2) { r0 = r0 * sh * g0[bj]; r1 = r1 * sh * g1[bj]; }
;                     const f32x4 v0 = r0 + acc[ai][bj][m][0], v1 = r1 + acc[ai][bj][m][1];
;                     if constexpr (WF32) { *(f32x4*)(out + (size_t)row * DM + c) = v0; *(f32x4*)(out + (size_t)row * DM + c + 4) = v1; }
;                     u32x4 w; w.x = pkbf(v0[0], v0[1]); w.y = pkbf(v0[2], v0[3]); w.z = pkbf(v1[0], v1[1]); w.w = pkbf(v1[2], v1[3]);
;                     *(u32x4*)(hb + (size_t)row * DM + c) = w;
;                     const f32x4 s0 = v0 * v0, s1 = v1 * v1;
;                     q += (s0[0] + s0[1]) + (s0[2] + s0[3]) + (s1[0] + s1[1]) + (s1[2] + s1[3]);
;                     if constexpr (MODE == 1) { const f32x4 t0 = s0 * g0[bj], t1 = s1 * g1[bj]; qw += (t0[0] + t0[1]) + (t0[2] + t0[3]) + (t1[0] + t1[1]) + (t1[2] + t1[3]); }
;                 }
;                 q += __shfl_xor(q, 16); q += __shfl_xor(q, 32);
;                 if constexpr (MODE == 1) { qw += __shfl_xor(qw, 16); qw += __shfl_xor(qw, 32); }
;                 if (fq == 0) {
;                     __hip_atomic_fetch_add(ssn + row, ss_fix(q), __ATOMIC_RELAXED, __HIP_MEMORY_SCOPE_AGENT);
;                     if constexpr (MODE == 1) __hip_atomic_fetch_add(ssw + row, ss_fix(qw), __ATOMIC_RELAXED, __HIP_MEMORY_SCOPE_AGENT);
;                 }
	v_lshlrev_b32_e32 v212, 16, v192
	v_and_b32_e32 v213, 0xffff0000, v192
	v_lshlrev_b32_e32 v214, 16, v193
	v_and_b32_e32 v215, 0xffff0000, v193
	v_lshlrev_b32_e32 v216, 16, v194
	v_and_b32_e32 v217, 0xffff0000, v194
	v_lshlrev_b32_e32 v218, 16, v195
	v_and_b32_e32 v219, 0xffff0000, v195
	v_pk_add_f32 v[76:77], v[76:77], v[212:213]
	v_pk_add_f32 v[78:79], v[78:79], v[214:215]
	v_pk_add_f32 v[72:73], v[72:73], v[216:217]
	v_pk_add_f32 v[74:75], v[74:75], v[218:219]
	v_lshlrev_b32_e32 v212, 16, v200
	v_and_b32_e32 v213, 0xffff0000, v200
	v_lshlrev_b32_e32 v214, 16, v201
	v_and_b32_e32 v215, 0xffff0000, v201
	v_lshlrev_b32_e32 v216, 16, v202
	v_and_b32_e32 v217, 0xffff0000, v202
	v_lshlrev_b32_e32 v218, 16, v203
	v_and_b32_e32 v219, 0xffff0000, v203
	v_pk_add_f32 v[68:69], v[68:69], v[212:213]
	v_pk_add_f32 v[70:71], v[70:71], v[214:215]
	v_pk_add_f32 v[64:65], v[64:65], v[216:217]
	v_pk_add_f32 v[66:67], v[66:67], v[218:219]
	v_pk_mul_f32 v[220:221], v[76:77], v[76:77]
	v_pk_fma_f32 v[220:221], v[78:79], v[78:79], v[220:221]
	v_pk_fma_f32 v[220:221], v[72:73], v[72:73], v[220:221]
	v_pk_fma_f32 v[220:221], v[74:75], v[74:75], v[220:221]
	v_pk_fma_f32 v[220:221], v[68:69], v[68:69], v[220:221]
	v_pk_fma_f32 v[220:221], v[70:71], v[70:71], v[220:221]
	v_pk_fma_f32 v[220:221], v[64:65], v[64:65], v[220:221]
	v_pk_fma_f32 v[220:221], v[66:67], v[66:67], v[220:221]
	v_add_f32_e32 v163, v220, v221
	s_nop 1
	v_permlane16_swap_b32_e32 v160, v161
	v_permlane16_swap_b32_e32 v162, v163
	v_add_f32_e32 v160, v160, v161
	v_add_f32_e32 v162, v162, v163
	s_nop 1
	v_permlane32_swap_b32_e32 v160, v162
	v_add_f32_e32 v160, v160, v162
	v_mul_f32_e32 v226, 0x4f800000, v160
	v_trunc_f32_e32 v226, v226
	v_mul_f32_e32 v227, 0x2f800000, v226
	v_floor_f32_e32 v227, v227
	v_fmac_f32_e32 v226, 0xcf800000, v227
	v_cvt_u32_f32_e32 v226, v226
	v_cvt_u32_f32_e32 v227, v227
	v_lshl_add_u64 v[224:225], v[222:223], 3, s[12:13]
	global_atomic_add_x2 v[224:225], v[226:227], off
	s_waitcnt vmcnt(7)
	v_lshlrev_b32_e32 v212, 16, v204
	v_and_b32_e32 v213, 0xffff0000, v204
	v_lshlrev_b32_e32 v214, 16, v205
	v_and_b32_e32 v215, 0xffff0000, v205
	v_lshlrev_b32_e32 v216, 16, v206
	v_and_b32_e32 v217, 0xffff0000, v206
	v_lshlrev_b32_e32 v218, 16, v207
	v_and_b32_e32 v219, 0xffff0000, v207
	v_pk_add_f32 v[60:61], v[60:61], v[212:213]
	v_pk_add_f32 v[62:63], v[62:63], v[214:215]
	v_pk_add_f32 v[56:57], v[56:57], v[216:217]
	v_pk_add_f32 v[58:59], v[58:59], v[218:219]
	v_lshlrev_b32_e32 v212, 16, v208
	v_and_b32_e32 v213, 0xffff0000, v208
	v_lshlrev_b32_e32 v214, 16, v209
	v_and_b32_e32 v215, 0xffff0000, v209
	v_lshlrev_b32_e32 v216, 16, v210
	v_and_b32_e32 v217, 0xffff0000, v210
	v_lshlrev_b32_e32 v218, 16, v211
	v_and_b32_e32 v219, 0xffff0000, v211
	v_pk_add_f32 v[52:53], v[52:53], v[212:213]
	v_pk_add_f32 v[54:55], v[54:55], v[214:215]
	v_pk_add_f32 v[48:49], v[48:49], v[216:217]
	v_pk_add_f32 v[50:51], v[50:51], v[218:219]
	v_pk_mul_f32 v[220:221], v[60:61], v[60:61]
	v_pk_fma_f32 v[220:221], v[62:63], v[62:63], v[220:221]
	v_pk_fma_f32 v[220:221], v[56:57], v[56:57], v[220:221]
	v_pk_fma_f32 v[220:221], v[58:59], v[58:59], v[220:221]
	v_pk_fma_f32 v[220:221], v[52:53], v[52:53], v[220:221]
	v_pk_fma_f32 v[220:221], v[54:55], v[54:55], v[220:221]
	v_pk_fma_f32 v[220:221], v[48:49], v[48:49], v[220:221]
	v_pk_fma_f32 v[220:221], v[50:51], v[50:51], v[220:221]
	v_add_f32_e32 v160, v220, v221
	s_waitcnt vmcnt(5)
	v_lshlrev_b32_e32 v212, 16, v168
	v_and_b32_e32 v213, 0xffff0000, v168
	v_lshlrev_b32_e32 v214, 16, v169
	v_and_b32_e32 v215, 0xffff0000, v169
	v_lshlrev_b32_e32 v216, 16, v170
	v_and_b32_e32 v217, 0xffff0000, v170
	v_lshlrev_b32_e32 v218, 16, v171
	v_and_b32_e32 v219, 0xffff0000, v171
	v_pk_add_f32 v[44:45], v[44:45], v[212:213]
	v_pk_add_f32 v[46:47], v[46:47], v[214:215]
	v_pk_add_f32 v[40:41], v[40:41], v[216:217]
	v_pk_add_f32 v[42:43], v[42:43], v[218:219]
	v_lshlrev_b32_e32 v212, 16, v172
	v_and_b32_e32 v213, 0xffff0000, v172
	v_lshlrev_b32_e32 v214, 16, v173
	v_and_b32_e32 v215, 0xffff0000, v173
	v_lshlrev_b32_e32 v216, 16, v174
	v_and_b32_e32 v217, 0xffff0000, v174
	v_lshlrev_b32_e32 v218, 16, v175
	v_and_b32_e32 v219, 0xffff0000, v175
	v_pk_add_f32 v[36:37], v[36:37], v[212:213]
	v_pk_add_f32 v[38:39], v[38:39], v[214:215]
	v_pk_add_f32 v[32:33], v[32:33], v[216:217]
	v_pk_add_f32 v[34:35], v[34:35], v[218:219]
	v_pk_mul_f32 v[220:221], v[44:45], v[44:45]
	v_pk_fma_f32 v[220:221], v[46:47], v[46:47], v[220:221]
	v_pk_fma_f32 v[220:221], v[40:41], v[40:41], v[220:221]
	v_pk_fma_f32 v[220:221], v[42:43], v[42:43], v[220:221]
	v_pk_fma_f32 v[220:221], v[36:37], v[36:37], v[220:221]
	v_pk_fma_f32 v[220:221], v[38:39], v[38:39], v[220:221]
	v_pk_fma_f32 v[220:221], v[32:33], v[32:33], v[220:221]
	v_pk_fma_f32 v[220:221], v[34:35], v[34:35], v[220:221]
	v_add_f32_e32 v161, v220, v221
	s_waitcnt vmcnt(3)
	v_lshlrev_b32_e32 v212, 16, v176
	v_and_b32_e32 v213, 0xffff0000, v176
	v_lshlrev_b32_e32 v214, 16, v177
	v_and_b32_e32 v215, 0xffff0000, v177
	v_lshlrev_b32_e32 v216, 16, v178
	v_and_b32_e32 v217, 0xffff0000, v178
	v_lshlrev_b32_e32 v218, 16, v179
	v_and_b32_e32 v219, 0xffff0000, v179
	v_pk_add_f32 v[28:29], v[28:29], v[212:213]
	v_pk_add_f32 v[30:31], v[30:31], v[214:215]
	v_pk_add_f32 v[24:25], v[24:25], v[216:217]
	v_pk_add_f32 v[26:27], v[26:27], v[218:219]
	v_lshlrev_b32_e32 v212, 16, v180
	v_and_b32_e32 v213, 0xffff0000, v180
	v_lshlrev_b32_e32 v214, 16, v181
	v_and_b32_e32 v215, 0xffff0000, v181
	v_lshlrev_b32_e32 v216, 16, v182
	v_and_b32_e32 v217, 0xffff0000, v182
	v_lshlrev_b32_e32 v218, 16, v183
	v_and_b32_e32 v219, 0xffff0000, v183
	v_pk_add_f32 v[20:21], v[20:21], v[212:213]
	v_pk_add_f32 v[22:23], v[22:23], v[214:215]
	v_pk_add_f32 v[16:17], v[16:17], v[216:217]
	v_pk_add_f32 v[18:19], v[18:19], v[218:219]
	v_pk_mul_f32 v[220:221], v[28:29], v[28:29]
	v_pk_fma_f32 v[220:221], v[30:31], v[30:31], v[220:221]
	v_pk_fma_f32 v[220:221], v[24:25], v[24:25], v[220:221]
	v_pk_fma_f32 v[220:221], v[26:27], v[26:27], v[220:221]
	v_pk_fma_f32 v[220:221], v[20:21], v[20:21], v[220:221]
	v_pk_fma_f32 v[220:221], v[22:23], v[22:23], v[220:221]
	v_pk_fma_f32 v[220:221], v[16:17], v[16:17], v[220:221]
	v_pk_fma_f32 v[220:221], v[18:19], v[18:19], v[220:221]
	v_add_f32_e32 v162, v220, v221
	s_waitcnt vmcnt(1)
; __device__ __forceinline__ u64 ss_fix(float q) { return (u64)(q * 4294967296.f); }
; __device__ __forceinline__ unsigned pkbf(float lo, float hi) { typedef __bf16 bf2_t __attribute__((ext_vector_type(2))); f32x2 v = {lo, hi}; bf2_t b = __builtin_convertvector(v, bf2_t); return __builtin_bit_cast(unsigned, b); }
;     __device__ __forceinline__ void operator()(const f32x4 (&acc)[2][2][4][2], const pg8::Unit& u, int wr, int wc, int fr, int fq) const {
;     ...
;                 for (int bj = 0; bj < 2; ++bj) {
;                     const int c = col0 + bj * 128;
;                     const u32x4 rb = *(const u32x4*)(hb + (size_t)row * DM + c);
;                     f32x4 r0 = {bflo(rb.x), bfhi(rb.x), bflo(rb.y), bfhi(rb.y)}, r1 = {bflo(rb.z), bfhi(rb.z), bflo(rb.w), bfhi(rb.w)};
;                     if constexpr (MODE == 2) { r0 = r0 * sh * g0[bj]; r1 = r1 * sh * g1[bj]; }
;                     const f32x4 v0 = r0 + acc[ai][bj][m][0], v1 = r1 + acc[ai][bj][m][1];
;                     if constexpr (WF32) { *(f32x4*)(out + (size_t)row * DM + c) = v0; *(f32x4*)(out + (size_t)row * DM + c + 4) = v1; }
;                     u32x4 w; w.x = pkbf(v0[0], v0[1]); w.y = pkbf(v0[2], v0[3]); w.z = pkbf(v1[0], v1[1]); w.w = pkbf(v1[2], v1[3]);
;                     *(u32x4*)(hb + (size_t)row * DM + c) = w;
;                     const f32x4 s0 = v0 * v0, s1 = v1 * v1;
;                     q += (s0[0] + s0[1]) + (s0[2] + s0[3]) + (s1[0] + s1[1]) + (s1[2] + s1[3]);
;                     if constexpr (MODE == 1) { const f32x4 t0 = s0 * g0[bj], t1 = s1 * g1[bj]; qw += (t0[0] + t0[1]) + (t0[2] + t0[3]) + (t1[0] + t1[1]) + (t1[2] + t1[3]); }
;                 }
;                 q += __shfl_xor(q, 16); q += __shfl_xor(q, 32);
;                 if constexpr (MODE == 1) { qw += __shfl_xor(qw, 16); qw += __shfl_xor(qw, 32); }
;                 if (fq == 0) {
;                     __hip_atomic_fetch_add(ssn + row, ss_fix(q), __ATOMIC_RELAXED, __HIP_MEMORY_SCOPE_AGENT);
;                     if constexpr (MODE == 1) __hip_atomic_fetch_add(ssw + row, ss_fix(qw), __ATOMIC_RELAXED, __HIP_MEMORY_SCOPE_AGENT);
;                 }
	v_lshlrev_b32_e32 v212, 16, v184
	v_and_b32_e32 v213, 0xffff0000, v184
	v_lshlrev_b32_e32 v214, 16, v185
	v_and_b32_e32 v215, 0xffff0000, v185
	v_lshlrev_b32_e32 v216, 16, v186
	v_and_b32_e32 v217, 0xffff0000, v186
	v_lshlrev_b32_e32 v218, 16, v187
	v_and_b32_e32 v219, 0xffff0000, v187
	v_pk_add_f32 v[12:13], v[12:13], v[212:213]
	v_pk_add_f32 v[14:15], v[14:15], v[214:215]
	v_pk_add_f32 v[8:9], v[8:9], v[216:217]
	v_pk_add_f32 v[10:11], v[10:11], v[218:219]
	v_lshlrev_b32_e32 v212, 16, v188
	v_and_b32_e32 v213, 0xffff0000, v188
	v_lshlrev_b32_e32 v214, 16, v189
	v_and_b32_e32 v215, 0xffff0000, v189
	v_lshlrev_b32_e32 v216, 16, v190
	v_and_b32_e32 v217, 0xffff0000, v190
	v_lshlrev_b32_e32 v218, 16, v191
	v_and_b32_e32 v219, 0xffff0000, v191
	v_pk_add_f32 v[4:5], v[4:5], v[212:213]
	v_pk_add_f32 v[6:7], v[6:7], v[214:215]
	v_pk_add_f32 v[0:1], v[0:1], v[216:217]
	v_pk_add_f32 v[2:3], v[2:3], v[218:219]
	v_pk_mul_f32 v[220:221], v[12:13], v[12:13]
	v_pk_fma_f32 v[220:221], v[14:15], v[14:15], v[220:221]
	v_pk_fma_f32 v[220:221], v[8:9], v[8:9], v[220:221]
	v_pk_fma_f32 v[220:221], v[10:11], v[10:11], v[220:221]
	v_pk_fma_f32 v[220:221], v[4:5], v[4:5], v[220:221]
	v_pk_fma_f32 v[220:221], v[6:7], v[6:7], v[220:221]
	v_pk_fma_f32 v[220:221], v[0:1], v[0:1], v[220:221]
	v_pk_fma_f32 v[220:221], v[2:3], v[2:3], v[220:221]
	v_add_f32_e32 v163, v220, v221
	s_nop 1
	v_permlane16_swap_b32_e32 v160, v161
	v_permlane16_swap_b32_e32 v162, v163
	v_add_f32_e32 v160, v160, v161
	v_add_f32_e32 v162, v162, v163
	s_nop 1
	v_permlane32_swap_b32_e32 v160, v162
	v_add_f32_e32 v160, v160, v162
	v_mul_f32_e32 v226, 0x4f800000, v160
	v_trunc_f32_e32 v226, v226
	v_mul_f32_e32 v227, 0x2f800000, v226
	v_floor_f32_e32 v227, v227
	v_fmac_f32_e32 v226, 0xcf800000, v227
	v_cvt_u32_f32_e32 v226, v226
	v_cvt_u32_f32_e32 v227, v227
	v_add_u32_e32 v222, 0x80, v222
	v_lshl_add_u64 v[224:225], v[222:223], 3, s[12:13]
	global_atomic_add_x2 v[224:225], v[226:227], off
	v_cvt_pk_bf16_f32 v124, v124, v125
	v_cvt_pk_bf16_f32 v125, v126, v127
	v_cvt_pk_bf16_f32 v126, v120, v121
	v_cvt_pk_bf16_f32 v127, v122, v123
	v_cvt_pk_bf16_f32 v116, v116, v117
	v_cvt_pk_bf16_f32 v117, v118, v119
	v_cvt_pk_bf16_f32 v118, v112, v113
	v_cvt_pk_bf16_f32 v119, v114, v115
	global_store_dwordx4 v[166:167], v[124:127], off
	global_store_dwordx4 v[166:167], v[116:119], off offset:256
	v_cvt_pk_bf16_f32 v108, v108, v109
	v_cvt_pk_bf16_f32 v109, v110, v111
	v_cvt_pk_bf16_f32 v110, v104, v105
	v_cvt_pk_bf16_f32 v111, v106, v107
	v_cvt_pk_bf16_f32 v100, v100, v101
	v_cvt_pk_bf16_f32 v101, v102, v103
	v_cvt_pk_bf16_f32 v102, v96, v97
	v_cvt_pk_bf16_f32 v103, v98, v99
	s_mov_b32 s100, 0x8000
	v_lshl_add_u64 v[158:159], v[166:167], 0, s[100:101]
	global_store_dwordx4 v[158:159], v[108:111], off
	global_store_dwordx4 v[158:159], v[100:103], off offset:256
	v_cvt_pk_bf16_f32 v92, v92, v93
	v_cvt_pk_bf16_f32 v93, v94, v95
	v_cvt_pk_bf16_f32 v94, v88, v89
	v_cvt_pk_bf16_f32 v95, v90, v91
	v_cvt_pk_bf16_f32 v84, v84, v85
	v_cvt_pk_bf16_f32 v85, v86, v87
	v_cvt_pk_bf16_f32 v86, v80, v81
	v_cvt_pk_bf16_f32 v87, v82, v83
	s_mov_b32 s100, 0x10000
	v_lshl_add_u64 v[158:159], v[166:167], 0, s[100:101]
	global_store_dwordx4 v[158:159], v[92:95], off
	global_store_dwordx4 v[158:159], v[84:87], off offset:256
	v_cvt_pk_bf16_f32 v76, v76, v77
	v_cvt_pk_bf16_f32 v77, v78, v79
	v_cvt_pk_bf16_f32 v78, v72, v73
	v_cvt_pk_bf16_f32 v79, v74, v75
	v_cvt_pk_bf16_f32 v68, v68, v69
	v_cvt_pk_bf16_f32 v69, v70, v71
	v_cvt_pk_bf16_f32 v70, v64, v65
	v_cvt_pk_bf16_f32 v71, v66, v67
	s_mov_b32 s100, 0x18000
	v_lshl_add_u64 v[158:159], v[166:167], 0, s[100:101]
	global_store_dwordx4 v[158:159], v[76:79], off
	global_store_dwordx4 v[158:159], v[68:71], off offset:256
	v_cvt_pk_bf16_f32 v60, v60, v61
	v_cvt_pk_bf16_f32 v61, v62, v63
	v_cvt_pk_bf16_f32 v62, v56, v57
	v_cvt_pk_bf16_f32 v63, v58, v59
	v_cvt_pk_bf16_f32 v52, v52, v53
	v_cvt_pk_bf16_f32 v53, v54, v55
	v_cvt_pk_bf16_f32 v54, v48, v49
	v_cvt_pk_bf16_f32 v55, v50, v51
	s_mov_b32 s100, 0x40000
	v_lshl_add_u64 v[158:159], v[166:167], 0, s[100:101]
	global_store_dwordx4 v[158:159], v[60:63], off
	global_store_dwordx4 v[158:159], v[52:55], off offset:256
	v_cvt_pk_bf16_f32 v44, v44, v45
	v_cvt_pk_bf16_f32 v45, v46, v47
	v_cvt_pk_bf16_f32 v46, v40, v41
	v_cvt_pk_bf16_f32 v47, v42, v43
	v_cvt_pk_bf16_f32 v36, v36, v37
	v_cvt_pk_bf16_f32 v37, v38, v39
	v_cvt_pk_bf16_f32 v38, v32, v33
	v_cvt_pk_bf16_f32 v39, v34, v35
	s_mov_b32 s100, 0x48000
	v_lshl_add_u64 v[158:159], v[166:167], 0, s[100:101]
	global_store_dwordx4 v[158:159], v[44:47], off
	global_store_dwordx4 v[158:159], v[36:39], off offset:256
	v_cvt_pk_bf16_f32 v28, v28, v29
	v_cvt_pk_bf16_f32 v29, v30, v31
	v_cvt_pk_bf16_f32 v30, v24, v25
	v_cvt_pk_bf16_f32 v31, v26, v27
	v_cvt_pk_bf16_f32 v20, v20, v21
	v_cvt_pk_bf16_f32 v21, v22, v23
	v_cvt_pk_bf16_f32 v22, v16, v17
	v_cvt_pk_bf16_f32 v23, v18, v19
	s_mov_b32 s100, 0x50000
	v_lshl_add_u64 v[158:159], v[166:167], 0, s[100:101]
	global_store_dwordx4 v[158:159], v[28:31], off
	global_store_dwordx4 v[158:159], v[20:23], off offset:256
	v_cvt_pk_bf16_f32 v12, v12, v13
	v_cvt_pk_bf16_f32 v13, v14, v15
	v_cvt_pk_bf16_f32 v14, v8, v9
	v_cvt_pk_bf16_f32 v15, v10, v11
	v_cvt_pk_bf16_f32 v4, v4, v5
	v_cvt_pk_bf16_f32 v5, v6, v7
	v_cvt_pk_bf16_f32 v6, v0, v1
	v_cvt_pk_bf16_f32 v7, v2, v3
	s_mov_b32 s100, 0x58000
	v_lshl_add_u64 v[158:159], v[166:167], 0, s[100:101]
	global_store_dwordx4 v[158:159], v[12:15], off
	global_store_dwordx4 v[158:159], v[4:7], off offset:256
	s_mov_b64 s[6:7], exec
